# v10_norm2
# speedup vs baseline: 1.0053x; 1.0053x over previous
; __device__ __forceinline__ void phase_norm(const Params& p, int l, int which, int bid, int G, int tid) {
;     ...
;     for (int row = wid * G + bid; row < T; row += 2 * G * 8) {
;         const int row2 = row + G * 8;
;         const float* xr = (l == 0 && which == 0) ? (row < TP ? p.in[0] + (size_t)row * D : p.in[1] + (size_t)(row - TP) * D) : p.out + (size_t)row * D;
;         const float* xr2 = (l == 0 && which == 0) ? (row2 < TP ? p.in[0] + (size_t)row2 * D : p.in[1] + (size_t)(row2 - TP) * D) : p.out + (size_t)row2 * D;
;         f32x4 v[8], v2[8]; float ss = 0.f, ss2 = 0.f;
; #pragma unroll
;         for (int i = 0; i < 8; ++i) { v[i] = *(const f32x4*)(xr + i * 256 + lane * 4); v2[i] = *(const f32x4*)(xr2 + i * 256 + lane * 4); }
; #pragma unroll
;         for (int i = 0; i < 8; ++i) { ss += v[i][0] * v[i][0] + v[i][1] * v[i][1] + v[i][2] * v[i][2] + v[i][3] * v[i][3]; ss2 += v2[i][0] * v2[i][0] + v2[i][1] * v2[i][1] + v2[i][2] * v2[i][2] + v2[i][3] * v2[i][3]; }
;         ss = wave_sum(ss); ss2 = wave_sum(ss2);
.LBB0_87:
	v_lshl_add_u64 v[34:35], v[110:111], 0, v[100:101]
	v_lshl_add_u64 v[36:37], v[102:103], 0, v[100:101]
	global_load_dwordx4 v[94:97], v[34:35], off
	global_load_dwordx4 v[90:93], v[36:37], off
	global_load_dwordx4 v[86:89], v[34:35], off offset:1024
	global_load_dwordx4 v[82:85], v[36:37], off offset:1024
	global_load_dwordx4 v[78:81], v[34:35], off offset:2048
	global_load_dwordx4 v[74:77], v[36:37], off offset:2048
	global_load_dwordx4 v[70:73], v[34:35], off offset:3072
	global_load_dwordx4 v[66:69], v[36:37], off offset:3072
	v_add_co_u32_e32 v34, vcc, s24, v34
	v_add_u32_e32 v113, s7, v98
	s_nop 0
	v_addc_co_u32_e32 v35, vcc, 0, v35, vcc
	global_load_dwordx4 v[62:65], v[34:35], off
	v_add_co_u32_e32 v36, vcc, s24, v36
	v_add_u32_e32 v99, s7, v151
	s_nop 0
	v_addc_co_u32_e32 v37, vcc, 0, v37, vcc
	global_load_dwordx4 v[58:61], v[36:37], off
	global_load_dwordx4 v[54:57], v[34:35], off offset:1024
	global_load_dwordx4 v[50:53], v[36:37], off offset:1024
	global_load_dwordx4 v[46:49], v[34:35], off offset:2048
	global_load_dwordx4 v[42:45], v[36:37], off offset:2048
	global_load_dwordx4 v[38:41], v[34:35], off offset:3072
	s_nop 0
	global_load_dwordx4 v[34:37], v[36:37], off offset:3072
	v_mov_b32_e32 v119, v0
	v_mov_b32_e32 v121, v0
	v_mov_b32_e32 v123, v0
	v_mov_b32_e32 v125, v0
	v_mov_b32_e32 v127, v0
	s_add_i32 s7, s7, s6
	v_lshl_add_u64 v[102:103], v[102:103], 0, s[8:9]
	v_lshl_add_u64 v[110:111], v[110:111], 0, s[8:9]
	s_waitcnt vmcnt(15)
	v_mov_b32_e32 v139, v95
	s_waitcnt vmcnt(14)
	v_mov_b32_e32 v138, v91
	v_pk_mul_f32 v[138:139], v[138:139], v[138:139]
	s_waitcnt vmcnt(12)
	v_mov_b32_e32 v140, v83
	v_mov_b32_e32 v141, v87
	v_pk_mul_f32 v[140:141], v[140:141], v[140:141]
	s_waitcnt vmcnt(6)
	v_mov_b32_e32 v136, v59
	v_mov_b32_e32 v134, v63
	s_waitcnt vmcnt(5)
	v_mov_b32_e32 v135, v55
	v_mov_b32_e32 v132, v62
	v_mov_b32_e32 v133, v54
	v_pk_mul_f32 v[134:135], v[134:135], v[134:135]
	s_waitcnt vmcnt(4)
	v_mov_b32_e32 v137, v51
	v_pk_fma_f32 v[132:133], v[132:133], v[132:133], v[134:135]
	v_mov_b32_e32 v134, v64
	v_mov_b32_e32 v135, v56
	v_pk_fma_f32 v[132:133], v[134:135], v[134:135], v[132:133]
	v_mov_b32_e32 v134, v65
	v_mov_b32_e32 v135, v57
	v_pk_fma_f32 v[132:133], v[134:135], v[134:135], v[132:133]
	v_mov_b32_e32 v134, v58
	v_mov_b32_e32 v135, v50
	v_pk_mul_f32 v[136:137], v[136:137], v[136:137]
	s_waitcnt vmcnt(2)
	v_mov_b32_e32 v142, v43
	v_pk_fma_f32 v[134:135], v[134:135], v[134:135], v[136:137]
	v_mov_b32_e32 v136, v60
	v_mov_b32_e32 v137, v52
	v_pk_fma_f32 v[134:135], v[136:137], v[136:137], v[134:135]
	v_mov_b32_e32 v136, v61
	v_mov_b32_e32 v137, v53
	v_pk_fma_f32 v[134:135], v[136:137], v[136:137], v[134:135]
	v_mov_b32_e32 v136, v90
	v_mov_b32_e32 v137, v94
	v_pk_fma_f32 v[136:137], v[136:137], v[136:137], v[138:139]
	v_mov_b32_e32 v138, v92
	v_mov_b32_e32 v139, v96
	v_pk_fma_f32 v[136:137], v[138:139], v[138:139], v[136:137]
	v_mov_b32_e32 v138, v93
	v_mov_b32_e32 v139, v97
	v_pk_fma_f32 v[136:137], v[138:139], v[138:139], v[136:137]
	v_mov_b32_e32 v138, v82
	v_mov_b32_e32 v139, v86
	v_pk_fma_f32 v[138:139], v[138:139], v[138:139], v[140:141]
	v_mov_b32_e32 v140, v84
	v_mov_b32_e32 v141, v88
	v_pk_fma_f32 v[138:139], v[140:141], v[140:141], v[138:139]
	v_mov_b32_e32 v140, v85
	v_mov_b32_e32 v141, v89
	v_pk_fma_f32 v[138:139], v[140:141], v[140:141], v[138:139]
	v_mov_b32_e32 v140, v75
	v_mov_b32_e32 v141, v79
	v_pk_add_f32 v[136:137], v[136:137], v[138:139]
	v_mov_b32_e32 v138, v74
	v_mov_b32_e32 v139, v78
	v_pk_mul_f32 v[140:141], v[140:141], v[140:141]
	s_waitcnt vmcnt(0)
	v_mov_b32_e32 v143, v35
	v_pk_fma_f32 v[138:139], v[138:139], v[138:139], v[140:141]
	v_mov_b32_e32 v140, v76
	v_mov_b32_e32 v141, v80
	v_pk_fma_f32 v[138:139], v[140:141], v[140:141], v[138:139]
	v_mov_b32_e32 v140, v77
	v_mov_b32_e32 v141, v81
	v_pk_fma_f32 v[138:139], v[140:141], v[140:141], v[138:139]
	v_mov_b32_e32 v140, v67
	v_mov_b32_e32 v141, v71
	v_pk_add_f32 v[136:137], v[136:137], v[138:139]
	v_mov_b32_e32 v138, v66
	v_mov_b32_e32 v139, v70
	v_pk_mul_f32 v[140:141], v[140:141], v[140:141]
	v_pk_mul_f32 v[142:143], v[142:143], v[142:143]
	v_pk_fma_f32 v[138:139], v[138:139], v[138:139], v[140:141]
	v_mov_b32_e32 v140, v68
	v_mov_b32_e32 v141, v72
	v_pk_fma_f32 v[138:139], v[140:141], v[140:141], v[138:139]
	v_mov_b32_e32 v140, v69
	v_mov_b32_e32 v141, v73
	v_pk_fma_f32 v[138:139], v[140:141], v[140:141], v[138:139]
	v_mov_b32_e32 v140, v47
	v_pk_add_f32 v[136:137], v[136:137], v[138:139]
	v_mov_b32_e32 v138, v134
	v_mov_b32_e32 v139, v132
	v_mov_b32_e32 v141, v39
	v_pk_add_f32 v[136:137], v[136:137], v[138:139]
	v_mov_b32_e32 v138, v46
	v_mov_b32_e32 v139, v38
	v_pk_mul_f32 v[140:141], v[140:141], v[140:141]
	v_mov_b32_e32 v132, v135
	v_pk_fma_f32 v[138:139], v[138:139], v[138:139], v[140:141]
	v_mov_b32_e32 v140, v48
	v_mov_b32_e32 v141, v40
	v_pk_fma_f32 v[138:139], v[140:141], v[140:141], v[138:139]
	v_mov_b32_e32 v140, v49
	v_mov_b32_e32 v141, v41
	v_pk_fma_f32 v[138:139], v[140:141], v[140:141], v[138:139]
	v_mov_b32_e32 v140, v42
	v_mov_b32_e32 v141, v34
	v_pk_fma_f32 v[140:141], v[140:141], v[140:141], v[142:143]
	v_mov_b32_e32 v142, v44
	v_mov_b32_e32 v143, v36
	v_pk_fma_f32 v[140:141], v[142:143], v[142:143], v[140:141]
	v_mov_b32_e32 v142, v45
	v_mov_b32_e32 v143, v37
	v_pk_fma_f32 v[140:141], v[142:143], v[142:143], v[140:141]
	v_pk_add_f32 v[132:133], v[136:137], v[132:133]
	v_mov_b32_e32 v134, v140
	v_mov_b32_e32 v135, v138
	v_pk_add_f32 v[132:133], v[132:133], v[134:135]
	v_mov_b32_e32 v138, v141
	v_pk_add_f32 v[132:133], v[132:133], v[138:139]
	ds_bpermute_b32 v135, v1, v133
	ds_bpermute_b32 v134, v1, v132
	s_waitcnt lgkmcnt(0)
; __device__ __forceinline__ unsigned pk2(float lo, float hi) { unsigned r; asm("v_cvt_pk_bf16_f32 %0, %1, %2" : "=v"(r) : "v"(lo), "v"(hi)); return r; }
; __device__ __forceinline__ void phase_norm(const Params& p, int l, int which, int bid, int G, int tid) {
;     ...
;         const float rs = rsqrtf(ss * (1.f / 2048.f) + 1e-6f), rs2 = rsqrtf(ss2 * (1.f / 2048.f) + 1e-6f);
;         const float* mb = mod + (size_t)(l * 6 + tok_batch(row)) * 12288 + which * 3 * 2048;
;         const float* mb2 = mod + (size_t)(l * 6 + tok_batch(row2)) * 12288 + which * 3 * 2048;
; #pragma unroll
;         for (int i = 0; i < 8; ++i) { const int col = i * 256 + lane * 4; const f32x4 g4 = gnr[i];
;             { const f32x4 sh = *(const f32x4*)(mb + col), sc = *(const f32x4*)(mb + 2048 + col);
;                 const f32x4 o = v[i] * rs * g4 * (sc + 1.f) + sh; u32x2 w; w.x = pk2(o[0], o[1]); w.y = pk2(o[2], o[3]); *(u32x2*)(act + (size_t)row * D + col) = w; }
;             { const f32x4 sh = *(const f32x4*)(mb2 + col), sc = *(const f32x4*)(mb2 + 2048 + col);
;                 const f32x4 o = v2[i] * rs2 * g4 * (sc + 1.f) + sh; u32x2 w; w.x = pk2(o[0], o[1]); w.y = pk2(o[2], o[3]); *(u32x2*)(act + (size_t)row2 * D + col) = w; } }
	v_pk_add_f32 v[132:133], v[132:133], v[134:135]
	ds_bpermute_b32 v135, v129, v133
	ds_bpermute_b32 v134, v129, v132
	s_waitcnt lgkmcnt(0)
	v_pk_add_f32 v[132:133], v[132:133], v[134:135]
	ds_bpermute_b32 v135, v131, v133
	ds_bpermute_b32 v134, v131, v132
	s_waitcnt lgkmcnt(0)
	v_pk_add_f32 v[132:133], v[132:133], v[134:135]
	ds_bpermute_b32 v135, v148, v133
	ds_bpermute_b32 v134, v148, v132
	s_waitcnt lgkmcnt(0)
	v_pk_add_f32 v[132:133], v[132:133], v[134:135]
	ds_bpermute_b32 v135, v149, v133
	ds_bpermute_b32 v134, v149, v132
	s_waitcnt lgkmcnt(0)
	v_pk_add_f32 v[132:133], v[132:133], v[134:135]
	ds_bpermute_b32 v135, v150, v133
	ds_bpermute_b32 v134, v150, v132
	s_waitcnt lgkmcnt(0)
	v_pk_add_f32 v[132:133], v[132:133], v[134:135]
	s_nop 0
	v_pk_fma_f32 v[132:133], v[132:133], s[14:15], v[178:179] op_sel_hi:[1,0,0]
	s_nop 0
	v_mul_f32_e32 v115, 0x4b800000, v133
	v_cmp_gt_f32_e64 s[0:1], s55, v133
	v_cmp_gt_f32_e32 vcc, s55, v132
	s_nop 0
	v_cndmask_b32_e64 v115, v133, v115, s[0:1]
	v_rsq_f32_e32 v115, v115
	s_nop 0
	v_mul_f32_e32 v117, 0x45800000, v115
	v_cndmask_b32_e64 v130, v115, v117, s[0:1]
	v_mul_f32_e32 v115, 0x4b800000, v132
	v_cndmask_b32_e32 v115, v132, v115, vcc
	v_rsq_f32_e32 v115, v115
	v_mov_b64_e32 v[132:133], s[22:23]
	v_pk_mul_f32 v[96:97], v[96:97], v[130:131] op_sel_hi:[1,0]
	v_pk_mul_f32 v[94:95], v[94:95], v[130:131] op_sel_hi:[1,0]
	v_mul_f32_e32 v117, 0x45800000, v115
	v_cndmask_b32_e32 v128, v115, v117, vcc
	v_cmp_gt_i32_e32 vcc, s2, v113
	v_ashrrev_i32_e32 v115, 13, v113
	v_add_u32_e32 v113, 0xffffc000, v113
	v_lshrrev_b32_e32 v113, 12, v113
	v_add_u32_e32 v113, 2, v113
	v_cndmask_b32_e32 v113, v113, v115, vcc
	v_add_u32_e32 v113, s3, v113
	v_mad_i64_i32 v[136:137], s[0:1], v113, s33, v[132:133]
	v_cmp_gt_i32_e32 vcc, s2, v99
	v_ashrrev_i32_e32 v113, 13, v99
	v_add_u32_e32 v99, 0xffffc000, v99
	v_lshrrev_b32_e32 v99, 12, v99
	v_add_u32_e32 v99, 2, v99
	v_cndmask_b32_e32 v99, v99, v113, vcc
	v_lshl_add_u64 v[138:139], v[136:137], 0, s[18:19]
	v_mov_b32_e32 v113, v0
	v_add_u32_e32 v99, s3, v99
	v_mad_i64_i32 v[134:135], s[0:1], v99, s33, v[132:133]
	v_mov_b32_e32 v115, v0
	v_mov_b32_e32 v117, v0
	v_lshl_add_u64 v[132:133], v[134:135], 0, s[18:19]
	v_lshl_add_u64 v[156:157], v[138:139], 0, v[112:113]
	v_lshl_add_u64 v[160:161], v[136:137], 0, v[112:113]
	global_load_dwordx4 v[156:159], v[156:157], off
	global_load_dwordx4 v[160:163], v[160:161], off
	v_lshl_add_u64 v[164:165], v[132:133], 0, v[112:113]
	v_lshl_add_u64 v[168:169], v[134:135], 0, v[112:113]
	global_load_dwordx4 v[164:167], v[164:165], off
	global_load_dwordx4 v[168:171], v[168:169], off
	v_lshl_add_u64 v[172:173], v[138:139], 0, v[114:115]
	v_lshl_add_u64 v[196:197], v[136:137], 0, v[114:115]
	global_load_dwordx4 v[172:175], v[172:173], off
	global_load_dwordx4 v[196:199], v[196:197], off
	v_lshl_add_u64 v[200:201], v[132:133], 0, v[114:115]
	v_lshl_add_u64 v[204:205], v[134:135], 0, v[114:115]
	global_load_dwordx4 v[200:203], v[200:201], off
	global_load_dwordx4 v[204:207], v[204:205], off
	v_lshl_add_u64 v[208:209], v[138:139], 0, v[116:117]
	v_lshl_add_u64 v[220:221], v[136:137], 0, v[116:117]
	global_load_dwordx4 v[208:211], v[208:209], off
	global_load_dwordx4 v[220:223], v[220:221], off
	v_lshl_add_u64 v[224:225], v[132:133], 0, v[116:117]
	v_lshl_add_u64 v[228:229], v[134:135], 0, v[116:117]
	global_load_dwordx4 v[224:227], v[224:225], off
	global_load_dwordx4 v[228:231], v[228:229], off
	v_lshl_add_u64 v[232:233], v[138:139], 0, v[118:119]
	v_lshl_add_u64 v[236:237], v[136:137], 0, v[118:119]
	global_load_dwordx4 v[232:235], v[232:233], off
	global_load_dwordx4 v[236:239], v[236:237], off
	v_lshl_add_u64 v[240:241], v[132:133], 0, v[118:119]
	v_lshl_add_u64 v[244:245], v[134:135], 0, v[118:119]
	global_load_dwordx4 v[240:243], v[240:241], off
	global_load_dwordx4 v[244:247], v[244:245], off
	v_pk_mul_f32 v[94:95], v[2:3], v[94:95]
	v_pk_mul_f32 v[96:97], v[4:5], v[96:97]
	v_pk_mul_f32 v[90:91], v[90:91], v[128:129] op_sel_hi:[1,0]
	v_pk_mul_f32 v[90:91], v[2:3], v[90:91]
	v_pk_mul_f32 v[92:93], v[92:93], v[128:129] op_sel_hi:[1,0]
	v_pk_mul_f32 v[92:93], v[4:5], v[92:93]
	v_pk_mul_f32 v[86:87], v[86:87], v[130:131] op_sel_hi:[1,0]
	v_pk_mul_f32 v[88:89], v[88:89], v[130:131] op_sel_hi:[1,0]
	v_pk_mul_f32 v[86:87], v[6:7], v[86:87]
	v_pk_mul_f32 v[88:89], v[8:9], v[88:89]
	v_pk_mul_f32 v[82:83], v[82:83], v[128:129] op_sel_hi:[1,0]
	v_pk_mul_f32 v[84:85], v[84:85], v[128:129] op_sel_hi:[1,0]
	v_pk_mul_f32 v[82:83], v[6:7], v[82:83]
	v_pk_mul_f32 v[84:85], v[8:9], v[84:85]
	v_pk_mul_f32 v[78:79], v[78:79], v[130:131] op_sel_hi:[1,0]
	v_pk_mul_f32 v[80:81], v[80:81], v[130:131] op_sel_hi:[1,0]
	v_pk_mul_f32 v[78:79], v[10:11], v[78:79]
	v_pk_mul_f32 v[80:81], v[12:13], v[80:81]
	v_pk_mul_f32 v[74:75], v[74:75], v[128:129] op_sel_hi:[1,0]
	v_pk_mul_f32 v[76:77], v[76:77], v[128:129] op_sel_hi:[1,0]
	v_pk_mul_f32 v[74:75], v[10:11], v[74:75]
	v_pk_mul_f32 v[76:77], v[12:13], v[76:77]
	v_pk_mul_f32 v[70:71], v[70:71], v[130:131] op_sel_hi:[1,0]
	v_pk_mul_f32 v[72:73], v[72:73], v[130:131] op_sel_hi:[1,0]
	v_pk_mul_f32 v[70:71], v[14:15], v[70:71]
	v_pk_mul_f32 v[72:73], v[16:17], v[72:73]
	v_pk_mul_f32 v[66:67], v[66:67], v[128:129] op_sel_hi:[1,0]
	v_pk_mul_f32 v[68:69], v[68:69], v[128:129] op_sel_hi:[1,0]
	v_pk_mul_f32 v[66:67], v[14:15], v[66:67]
	v_pk_mul_f32 v[68:69], v[16:17], v[68:69]
	v_pk_mul_f32 v[62:63], v[62:63], v[130:131] op_sel_hi:[1,0]
	v_pk_mul_f32 v[64:65], v[64:65], v[130:131] op_sel_hi:[1,0]
	v_pk_mul_f32 v[62:63], v[18:19], v[62:63]
	v_pk_mul_f32 v[64:65], v[20:21], v[64:65]
	v_pk_mul_f32 v[58:59], v[58:59], v[128:129] op_sel_hi:[1,0]
; __device__ __forceinline__ unsigned pk2(float lo, float hi) { unsigned r; asm("v_cvt_pk_bf16_f32 %0, %1, %2" : "=v"(r) : "v"(lo), "v"(hi)); return r; }
; __device__ __forceinline__ void phase_norm(const Params& p, int l, int which, int bid, int G, int tid) {
;     ...
;         for (int i = 0; i < 8; ++i) { const int col = i * 256 + lane * 4; const f32x4 g4 = gnr[i];
;             { const f32x4 sh = *(const f32x4*)(mb + col), sc = *(const f32x4*)(mb + 2048 + col);
;                 const f32x4 o = v[i] * rs * g4 * (sc + 1.f) + sh; u32x2 w; w.x = pk2(o[0], o[1]); w.y = pk2(o[2], o[3]); *(u32x2*)(act + (size_t)row * D + col) = w; }
;             { const f32x4 sh = *(const f32x4*)(mb2 + col), sc = *(const f32x4*)(mb2 + 2048 + col);
;                 const f32x4 o = v2[i] * rs2 * g4 * (sc + 1.f) + sh; u32x2 w; w.x = pk2(o[0], o[1]); w.y = pk2(o[2], o[3]); *(u32x2*)(act + (size_t)row2 * D + col) = w; } }
	v_pk_mul_f32 v[60:61], v[60:61], v[128:129] op_sel_hi:[1,0]
	v_pk_mul_f32 v[58:59], v[18:19], v[58:59]
	v_pk_mul_f32 v[60:61], v[20:21], v[60:61]
	v_pk_mul_f32 v[54:55], v[54:55], v[130:131] op_sel_hi:[1,0]
	v_pk_mul_f32 v[56:57], v[56:57], v[130:131] op_sel_hi:[1,0]
	v_pk_mul_f32 v[54:55], v[22:23], v[54:55]
	v_pk_mul_f32 v[56:57], v[24:25], v[56:57]
	v_pk_mul_f32 v[50:51], v[50:51], v[128:129] op_sel_hi:[1,0]
	v_pk_mul_f32 v[52:53], v[52:53], v[128:129] op_sel_hi:[1,0]
	v_pk_mul_f32 v[50:51], v[22:23], v[50:51]
	v_pk_mul_f32 v[52:53], v[24:25], v[52:53]
	v_pk_mul_f32 v[46:47], v[46:47], v[130:131] op_sel_hi:[1,0]
	v_pk_mul_f32 v[48:49], v[48:49], v[130:131] op_sel_hi:[1,0]
	v_pk_mul_f32 v[46:47], v[26:27], v[46:47]
	v_pk_mul_f32 v[48:49], v[28:29], v[48:49]
	v_pk_mul_f32 v[42:43], v[42:43], v[128:129] op_sel_hi:[1,0]
	v_pk_mul_f32 v[44:45], v[44:45], v[128:129] op_sel_hi:[1,0]
	v_pk_mul_f32 v[42:43], v[26:27], v[42:43]
	v_pk_mul_f32 v[44:45], v[28:29], v[44:45]
	v_pk_mul_f32 v[38:39], v[38:39], v[130:131] op_sel_hi:[1,0]
	v_pk_mul_f32 v[40:41], v[40:41], v[130:131] op_sel_hi:[1,0]
	v_pk_mul_f32 v[38:39], v[30:31], v[38:39]
	v_pk_mul_f32 v[40:41], v[32:33], v[40:41]
	v_pk_mul_f32 v[34:35], v[34:35], v[128:129] op_sel_hi:[1,0]
	v_pk_mul_f32 v[36:37], v[36:37], v[128:129] op_sel_hi:[1,0]
	v_pk_mul_f32 v[34:35], v[30:31], v[34:35]
	v_pk_mul_f32 v[36:37], v[32:33], v[36:37]
	s_mov_b32 s0, 0x6000000
	v_lshl_add_u64 v[176:177], v[106:107], 0, v[104:105]
	v_lshl_add_u64 v[214:215], v[108:109], 0, v[104:105]
	v_lshl_add_u64 v[106:107], v[106:107], 0, s[10:11]
	v_add_co_u32_e32 v214, vcc, s0, v214
	v_lshl_add_u64 v[108:109], v[108:109], 0, s[10:11]
	s_nop 0
	v_addc_co_u32_e32 v215, vcc, 0, v215, vcc
	s_waitcnt vmcnt(14)
	v_pk_add_f32 v[156:157], v[156:157], 1.0 op_sel_hi:[1,0]
	v_pk_add_f32 v[158:159], v[158:159], 1.0 op_sel_hi:[1,0]
	v_pk_fma_f32 v[94:95], v[94:95], v[156:157], v[160:161]
	v_pk_fma_f32 v[96:97], v[96:97], v[158:159], v[162:163]
	v_cvt_pk_bf16_f32 v94, v94, v95
	v_cvt_pk_bf16_f32 v95, v96, v97
	global_store_dwordx2 v[176:177], v[94:95], off offset:-2048
	v_lshl_add_u64 v[156:157], v[138:139], 0, v[120:121]
	v_lshl_add_u64 v[160:161], v[136:137], 0, v[120:121]
	global_load_dwordx4 v[156:159], v[156:157], off
	global_load_dwordx4 v[160:163], v[160:161], off
	s_waitcnt vmcnt(15)
	v_pk_add_f32 v[164:165], v[164:165], 1.0 op_sel_hi:[1,0]
	v_pk_add_f32 v[166:167], v[166:167], 1.0 op_sel_hi:[1,0]
	v_pk_fma_f32 v[90:91], v[90:91], v[164:165], v[168:169]
	v_pk_fma_f32 v[92:93], v[92:93], v[166:167], v[170:171]
	v_cvt_pk_bf16_f32 v90, v90, v91
	v_cvt_pk_bf16_f32 v91, v92, v93
	global_store_dwordx2 v[214:215], v[90:91], off
	v_lshl_add_u64 v[164:165], v[132:133], 0, v[120:121]
	v_lshl_add_u64 v[168:169], v[134:135], 0, v[120:121]
	global_load_dwordx4 v[164:167], v[164:165], off
	global_load_dwordx4 v[168:171], v[168:169], off
	s_waitcnt vmcnt(16)
	v_pk_add_f32 v[172:173], v[172:173], 1.0 op_sel_hi:[1,0]
	v_pk_add_f32 v[174:175], v[174:175], 1.0 op_sel_hi:[1,0]
	v_pk_fma_f32 v[86:87], v[86:87], v[172:173], v[196:197]
	v_pk_fma_f32 v[88:89], v[88:89], v[174:175], v[198:199]
	v_cvt_pk_bf16_f32 v86, v86, v87
	v_cvt_pk_bf16_f32 v87, v88, v89
	global_store_dwordx2 v[176:177], v[86:87], off offset:-1536
	v_lshl_add_u64 v[172:173], v[138:139], 0, v[122:123]
	v_lshl_add_u64 v[196:197], v[136:137], 0, v[122:123]
	global_load_dwordx4 v[172:175], v[172:173], off
	global_load_dwordx4 v[196:199], v[196:197], off
	s_waitcnt vmcnt(17)
	v_pk_add_f32 v[200:201], v[200:201], 1.0 op_sel_hi:[1,0]
	v_pk_add_f32 v[202:203], v[202:203], 1.0 op_sel_hi:[1,0]
	v_pk_fma_f32 v[82:83], v[82:83], v[200:201], v[204:205]
	v_pk_fma_f32 v[84:85], v[84:85], v[202:203], v[206:207]
	v_cvt_pk_bf16_f32 v82, v82, v83
	v_cvt_pk_bf16_f32 v83, v84, v85
	global_store_dwordx2 v[214:215], v[82:83], off offset:512
	v_lshl_add_u64 v[200:201], v[132:133], 0, v[122:123]
	v_lshl_add_u64 v[204:205], v[134:135], 0, v[122:123]
	global_load_dwordx4 v[200:203], v[200:201], off
	global_load_dwordx4 v[204:207], v[204:205], off
	s_waitcnt vmcnt(18)
	v_pk_add_f32 v[208:209], v[208:209], 1.0 op_sel_hi:[1,0]
	v_pk_add_f32 v[210:211], v[210:211], 1.0 op_sel_hi:[1,0]
	v_pk_fma_f32 v[78:79], v[78:79], v[208:209], v[220:221]
	v_pk_fma_f32 v[80:81], v[80:81], v[210:211], v[222:223]
	v_cvt_pk_bf16_f32 v78, v78, v79
	v_cvt_pk_bf16_f32 v79, v80, v81
	global_store_dwordx2 v[176:177], v[78:79], off offset:-1024
	v_lshl_add_u64 v[208:209], v[138:139], 0, v[124:125]
	v_lshl_add_u64 v[220:221], v[136:137], 0, v[124:125]
	global_load_dwordx4 v[208:211], v[208:209], off
	global_load_dwordx4 v[220:223], v[220:221], off
	s_waitcnt vmcnt(19)
; __device__ __forceinline__ unsigned pk2(float lo, float hi) { unsigned r; asm("v_cvt_pk_bf16_f32 %0, %1, %2" : "=v"(r) : "v"(lo), "v"(hi)); return r; }
; __device__ __forceinline__ void phase_norm(const Params& p, int l, int which, int bid, int G, int tid) {
;     ...
;         for (int i = 0; i < 8; ++i) { const int col = i * 256 + lane * 4; const f32x4 g4 = gnr[i];
;             { const f32x4 sh = *(const f32x4*)(mb + col), sc = *(const f32x4*)(mb + 2048 + col);
;                 const f32x4 o = v[i] * rs * g4 * (sc + 1.f) + sh; u32x2 w; w.x = pk2(o[0], o[1]); w.y = pk2(o[2], o[3]); *(u32x2*)(act + (size_t)row * D + col) = w; }
;             { const f32x4 sh = *(const f32x4*)(mb2 + col), sc = *(const f32x4*)(mb2 + 2048 + col);
;                 const f32x4 o = v2[i] * rs2 * g4 * (sc + 1.f) + sh; u32x2 w; w.x = pk2(o[0], o[1]); w.y = pk2(o[2], o[3]); *(u32x2*)(act + (size_t)row2 * D + col) = w; } }
;     }
	v_pk_add_f32 v[224:225], v[224:225], 1.0 op_sel_hi:[1,0]
	v_pk_add_f32 v[226:227], v[226:227], 1.0 op_sel_hi:[1,0]
	v_pk_fma_f32 v[74:75], v[74:75], v[224:225], v[228:229]
	v_pk_fma_f32 v[76:77], v[76:77], v[226:227], v[230:231]
	v_cvt_pk_bf16_f32 v74, v74, v75
	v_cvt_pk_bf16_f32 v75, v76, v77
	global_store_dwordx2 v[214:215], v[74:75], off offset:1024
	v_lshl_add_u64 v[224:225], v[132:133], 0, v[124:125]
	v_lshl_add_u64 v[228:229], v[134:135], 0, v[124:125]
	global_load_dwordx4 v[224:227], v[224:225], off
	global_load_dwordx4 v[228:231], v[228:229], off
	s_waitcnt vmcnt(20)
	v_pk_add_f32 v[232:233], v[232:233], 1.0 op_sel_hi:[1,0]
	v_pk_add_f32 v[234:235], v[234:235], 1.0 op_sel_hi:[1,0]
	v_pk_fma_f32 v[70:71], v[70:71], v[232:233], v[236:237]
	v_pk_fma_f32 v[72:73], v[72:73], v[234:235], v[238:239]
	v_cvt_pk_bf16_f32 v70, v70, v71
	v_cvt_pk_bf16_f32 v71, v72, v73
	global_store_dwordx2 v[176:177], v[70:71], off offset:-512
	v_lshl_add_u64 v[232:233], v[138:139], 0, v[126:127]
	v_lshl_add_u64 v[236:237], v[136:137], 0, v[126:127]
	global_load_dwordx4 v[232:235], v[232:233], off
	global_load_dwordx4 v[236:239], v[236:237], off
	s_waitcnt vmcnt(21)
	v_pk_add_f32 v[240:241], v[240:241], 1.0 op_sel_hi:[1,0]
	v_pk_add_f32 v[242:243], v[242:243], 1.0 op_sel_hi:[1,0]
	v_pk_fma_f32 v[66:67], v[66:67], v[240:241], v[244:245]
	v_pk_fma_f32 v[68:69], v[68:69], v[242:243], v[246:247]
	v_cvt_pk_bf16_f32 v66, v66, v67
	v_cvt_pk_bf16_f32 v67, v68, v69
	global_store_dwordx2 v[214:215], v[66:67], off offset:1536
	v_lshl_add_u64 v[240:241], v[132:133], 0, v[126:127]
	v_lshl_add_u64 v[244:245], v[134:135], 0, v[126:127]
	global_load_dwordx4 v[240:243], v[240:241], off
	global_load_dwordx4 v[244:247], v[244:245], off
	s_waitcnt vmcnt(21)
	v_pk_add_f32 v[156:157], v[156:157], 1.0 op_sel_hi:[1,0]
	v_pk_add_f32 v[158:159], v[158:159], 1.0 op_sel_hi:[1,0]
	v_pk_fma_f32 v[62:63], v[62:63], v[156:157], v[160:161]
	v_pk_fma_f32 v[64:65], v[64:65], v[158:159], v[162:163]
	v_cvt_pk_bf16_f32 v62, v62, v63
	v_cvt_pk_bf16_f32 v63, v64, v65
	global_store_dwordx2 v[176:177], v[62:63], off
	s_waitcnt vmcnt(19)
	v_pk_add_f32 v[164:165], v[164:165], 1.0 op_sel_hi:[1,0]
	v_pk_add_f32 v[166:167], v[166:167], 1.0 op_sel_hi:[1,0]
	v_pk_fma_f32 v[58:59], v[58:59], v[164:165], v[168:169]
	v_pk_fma_f32 v[60:61], v[60:61], v[166:167], v[170:171]
	v_cvt_pk_bf16_f32 v58, v58, v59
	v_cvt_pk_bf16_f32 v59, v60, v61
	global_store_dwordx2 v[214:215], v[58:59], off offset:2048
	s_waitcnt vmcnt(17)
	v_pk_add_f32 v[172:173], v[172:173], 1.0 op_sel_hi:[1,0]
	v_pk_add_f32 v[174:175], v[174:175], 1.0 op_sel_hi:[1,0]
	v_pk_fma_f32 v[54:55], v[54:55], v[172:173], v[196:197]
	v_pk_fma_f32 v[56:57], v[56:57], v[174:175], v[198:199]
	v_cvt_pk_bf16_f32 v54, v54, v55
	v_cvt_pk_bf16_f32 v55, v56, v57
	global_store_dwordx2 v[176:177], v[54:55], off offset:512
	s_waitcnt vmcnt(15)
	v_pk_add_f32 v[200:201], v[200:201], 1.0 op_sel_hi:[1,0]
	v_pk_add_f32 v[202:203], v[202:203], 1.0 op_sel_hi:[1,0]
	v_pk_fma_f32 v[50:51], v[50:51], v[200:201], v[204:205]
	v_pk_fma_f32 v[52:53], v[52:53], v[202:203], v[206:207]
	v_cvt_pk_bf16_f32 v50, v50, v51
	v_cvt_pk_bf16_f32 v51, v52, v53
	global_store_dwordx2 v[214:215], v[50:51], off offset:2560
	s_waitcnt vmcnt(13)
	v_pk_add_f32 v[208:209], v[208:209], 1.0 op_sel_hi:[1,0]
	v_pk_add_f32 v[210:211], v[210:211], 1.0 op_sel_hi:[1,0]
	v_pk_fma_f32 v[46:47], v[46:47], v[208:209], v[220:221]
	v_pk_fma_f32 v[48:49], v[48:49], v[210:211], v[222:223]
	v_cvt_pk_bf16_f32 v46, v46, v47
	v_cvt_pk_bf16_f32 v47, v48, v49
	global_store_dwordx2 v[176:177], v[46:47], off offset:1024
	s_waitcnt vmcnt(11)
	v_pk_add_f32 v[224:225], v[224:225], 1.0 op_sel_hi:[1,0]
	v_pk_add_f32 v[226:227], v[226:227], 1.0 op_sel_hi:[1,0]
	v_pk_fma_f32 v[42:43], v[42:43], v[224:225], v[228:229]
	v_pk_fma_f32 v[44:45], v[44:45], v[226:227], v[230:231]
	v_cvt_pk_bf16_f32 v42, v42, v43
	v_cvt_pk_bf16_f32 v43, v44, v45
	global_store_dwordx2 v[214:215], v[42:43], off offset:3072
	s_waitcnt vmcnt(9)
	v_pk_add_f32 v[232:233], v[232:233], 1.0 op_sel_hi:[1,0]
	v_pk_add_f32 v[234:235], v[234:235], 1.0 op_sel_hi:[1,0]
	v_pk_fma_f32 v[38:39], v[38:39], v[232:233], v[236:237]
	v_pk_fma_f32 v[40:41], v[40:41], v[234:235], v[238:239]
	v_cvt_pk_bf16_f32 v38, v38, v39
	v_cvt_pk_bf16_f32 v39, v40, v41
	global_store_dwordx2 v[176:177], v[38:39], off offset:1536
	s_waitcnt vmcnt(7)
	v_pk_add_f32 v[240:241], v[240:241], 1.0 op_sel_hi:[1,0]
	v_pk_add_f32 v[242:243], v[242:243], 1.0 op_sel_hi:[1,0]
	v_pk_fma_f32 v[34:35], v[34:35], v[240:241], v[244:245]
	v_pk_fma_f32 v[36:37], v[36:37], v[242:243], v[246:247]
	v_cvt_pk_bf16_f32 v34, v34, v35
	v_cvt_pk_bf16_f32 v35, v36, v37
	global_store_dwordx2 v[214:215], v[34:35], off offset:3584
	v_add_u32_e32 v34, s7, v98
	v_cmp_lt_i32_e32 vcc, s46, v34
	s_or_b64 s[12:13], vcc, s[12:13]
	s_andn2_b64 exec, exec, s[12:13]
	s_cbranch_execnz .LBB0_87
